# P0 modulation loads hoisted (both variants); init GEMV loop unrolled x2 with 16 weight loads in flight
# speedup vs baseline: 1.0191x; 1.0001x over previous
; #define LAS __attribute__((address_space(3)))
; __device__ __forceinline__ void phase_init(const Frame& F, ArgsRef A) {
;     ...
;         const float* wp = ada_w + ((size_t)l * 2048 + F.wave * 256) * 18432 + col;
;         const LAS float* sp = sc + F.wave * 256;
; #pragma unroll 8
;         for (int k = 0; k < 256; ++k) { const f32x2 w = *(const f32x2*)(wp + (size_t)k * 18432);
; #pragma unroll
;             for (int bs = 0; bs < 9; ++bs) { const float s = sp[bs * 2048 + k]; a0[bs] += s * w.x; a1[bs] += s * w.y; } }
.LBB0_16:
	v_add_co_u32_e64 v26, s[2:3], s19, v6
	global_load_dwordx2 v[100:101], v[6:7], off
	s_nop 0
	v_addc_co_u32_e64 v27, s[2:3], -1, v7, s[2:3]
	v_add_co_u32_e64 v28, s[2:3], s20, v6
	s_add_i32 s9, s12, s8
	s_nop 0
	v_addc_co_u32_e64 v29, s[2:3], -1, v7, s[2:3]
	v_add_co_u32_e64 v30, s[2:3], s21, v6
	v_mov_b32_e32 v88, s9
	s_nop 0
	v_addc_co_u32_e64 v31, s[2:3], -1, v7, s[2:3]
	v_add_co_u32_e64 v32, s[2:3], s22, v6
	s_add_i32 s8, s8, 32
	s_nop 0
	v_addc_co_u32_e64 v33, s[2:3], -1, v7, s[2:3]
	v_add_co_u32_e64 v36, s[2:3], s13, v6
	global_load_dwordx2 v[102:103], v[26:27], off
	global_load_dwordx2 v[104:105], v[28:29], off
	global_load_dwordx2 v[106:107], v[30:31], off
	global_load_dwordx2 v[108:109], v[32:33], off
	v_addc_co_u32_e64 v37, s[2:3], 0, v7, s[2:3]
	v_add_co_u32_e64 v38, s[2:3], s23, v6
	s_nop 1
	v_addc_co_u32_e64 v39, s[2:3], 0, v7, s[2:3]
	v_add_co_u32_e64 v40, s[2:3], s24, v6
	s_nop 1
	v_addc_co_u32_e64 v41, s[2:3], 0, v7, s[2:3]
	global_load_dwordx2 v[110:111], v[36:37], off
	global_load_dwordx2 v[112:113], v[38:39], off
	global_load_dwordx2 v[114:115], v[40:41], off
	s_add_i32 s2, s9, 0x10000
	s_add_i32 s3, s9, 0x10010
	v_mov_b32_e32 v92, s2
	v_mov_b32_e32 v96, s3
	v_lshl_add_u64 v[168:169], v[6:7], 0, s[4:5]
	v_add_co_u32_e64 v170, s[2:3], s19, v168
	global_load_dwordx2 v[152:153], v[168:169], off
	s_nop 0
	v_addc_co_u32_e64 v171, s[2:3], -1, v169, s[2:3]
	v_add_co_u32_e64 v172, s[2:3], s20, v168
	s_nop 0
	s_nop 0
	v_addc_co_u32_e64 v173, s[2:3], -1, v169, s[2:3]
	v_add_co_u32_e64 v174, s[2:3], s21, v168
	s_nop 0
	s_nop 0
	v_addc_co_u32_e64 v175, s[2:3], -1, v169, s[2:3]
	v_add_co_u32_e64 v176, s[2:3], s22, v168
	s_nop 0
	s_nop 0
	v_addc_co_u32_e64 v177, s[2:3], -1, v169, s[2:3]
	v_add_co_u32_e64 v178, s[2:3], s13, v168
	global_load_dwordx2 v[154:155], v[170:171], off
	global_load_dwordx2 v[156:157], v[172:173], off
	global_load_dwordx2 v[158:159], v[174:175], off
	global_load_dwordx2 v[160:161], v[176:177], off
	v_addc_co_u32_e64 v179, s[2:3], 0, v169, s[2:3]
	v_add_co_u32_e64 v180, s[2:3], s23, v168
	s_nop 1
	v_addc_co_u32_e64 v181, s[2:3], 0, v169, s[2:3]
	v_add_co_u32_e64 v182, s[2:3], s24, v168
	s_nop 1
	v_addc_co_u32_e64 v183, s[2:3], 0, v169, s[2:3]
	global_load_dwordx2 v[162:163], v[178:179], off
	global_load_dwordx2 v[164:165], v[180:181], off
	global_load_dwordx2 v[166:167], v[182:183], off
	s_nop 0
	s_nop 0
	s_nop 0
	s_nop 0
	ds_read_b128 v[26:29], v88
	ds_read_b128 v[30:33], v88 offset:16
	ds_read_b128 v[36:39], v88 offset:8192
	ds_read_b128 v[40:43], v88 offset:8208
	ds_read_b128 v[44:47], v88 offset:16384
	ds_read_b128 v[48:51], v88 offset:16400
	ds_read_b128 v[52:55], v88 offset:24576
	ds_read_b128 v[56:59], v88 offset:24592
	ds_read_b128 v[60:63], v88 offset:32768
	ds_read_b128 v[64:67], v88 offset:32784
	ds_read_b128 v[68:71], v88 offset:40960
	ds_read_b128 v[72:75], v88 offset:40976
	ds_read_b128 v[76:79], v88 offset:49152
	ds_read_b128 v[80:83], v88 offset:49168
	ds_read_b128 v[84:87], v88 offset:57344
	ds_read_b128 v[88:91], v88 offset:57360
	ds_read_b128 v[92:95], v92
	ds_read_b128 v[96:99], v96
	s_waitcnt lgkmcnt(14)
	v_mov_b32_e32 v116, v29
	v_mov_b32_e32 v118, v39
	s_waitcnt lgkmcnt(13)
	v_mov_b32_e32 v120, v47
	s_waitcnt lgkmcnt(11)
	v_mov_b32_e32 v122, v55
	s_waitcnt lgkmcnt(9)
	v_mov_b32_e32 v124, v63
	s_waitcnt lgkmcnt(7)
	v_mov_b32_e32 v126, v71
	s_waitcnt lgkmcnt(5)
	v_mov_b32_e32 v128, v79
	s_waitcnt lgkmcnt(3)
	v_mov_b32_e32 v130, v87
	s_waitcnt lgkmcnt(1)
	v_mov_b32_e32 v148, v95
	v_mov_b32_e32 v132, v33
	v_mov_b32_e32 v134, v43
	v_mov_b32_e32 v136, v51
	v_mov_b32_e32 v138, v59
	v_mov_b32_e32 v140, v67
	v_mov_b32_e32 v142, v75
	v_mov_b32_e32 v144, v83
	v_mov_b32_e32 v146, v91
	s_waitcnt lgkmcnt(0)
	v_mov_b32_e32 v150, v99
	v_lshl_add_u64 v[6:7], v[6:7], 0, s[4:5]
	s_waitcnt vmcnt(14)
	v_pk_fma_f32 v[8:9], v[102:103], v[26:27], v[8:9] op_sel_hi:[1,0,1]
	v_pk_fma_f32 v[12:13], v[102:103], v[36:37], v[12:13] op_sel_hi:[1,0,1]
	v_pk_fma_f32 v[10:11], v[102:103], v[44:45], v[10:11] op_sel_hi:[1,0,1]
	v_pk_fma_f32 v[16:17], v[102:103], v[52:53], v[16:17] op_sel_hi:[1,0,1]
	v_pk_fma_f32 v[14:15], v[102:103], v[60:61], v[14:15] op_sel_hi:[1,0,1]
	v_pk_fma_f32 v[20:21], v[102:103], v[68:69], v[20:21] op_sel_hi:[1,0,1]
	v_pk_fma_f32 v[18:19], v[102:103], v[76:77], v[18:19] op_sel_hi:[1,0,1]
	v_pk_fma_f32 v[24:25], v[102:103], v[84:85], v[24:25] op_sel_hi:[1,0,1]
	v_pk_fma_f32 v[22:23], v[102:103], v[92:93], v[22:23] op_sel_hi:[1,0,1]
	s_waitcnt vmcnt(13)
	v_pk_fma_f32 v[8:9], v[104:105], v[26:27], v[8:9] op_sel:[0,1,0]
	v_pk_fma_f32 v[12:13], v[104:105], v[36:37], v[12:13] op_sel:[0,1,0]
	v_pk_fma_f32 v[10:11], v[104:105], v[44:45], v[10:11] op_sel:[0,1,0]
	v_pk_fma_f32 v[16:17], v[104:105], v[52:53], v[16:17] op_sel:[0,1,0]
	v_pk_fma_f32 v[14:15], v[104:105], v[60:61], v[14:15] op_sel:[0,1,0]
	v_pk_fma_f32 v[20:21], v[104:105], v[68:69], v[20:21] op_sel:[0,1,0]
	v_pk_fma_f32 v[18:19], v[104:105], v[76:77], v[18:19] op_sel:[0,1,0]
	v_pk_fma_f32 v[24:25], v[104:105], v[84:85], v[24:25] op_sel:[0,1,0]
	v_pk_fma_f32 v[22:23], v[104:105], v[92:93], v[22:23] op_sel:[0,1,0]
	s_waitcnt vmcnt(12)
	v_pk_fma_f32 v[8:9], v[106:107], v[28:29], v[8:9] op_sel_hi:[1,0,1]
	v_pk_fma_f32 v[12:13], v[106:107], v[38:39], v[12:13] op_sel_hi:[1,0,1]
	v_pk_fma_f32 v[10:11], v[106:107], v[46:47], v[10:11] op_sel_hi:[1,0,1]
	v_pk_fma_f32 v[16:17], v[106:107], v[54:55], v[16:17] op_sel_hi:[1,0,1]
	v_pk_fma_f32 v[14:15], v[106:107], v[62:63], v[14:15] op_sel_hi:[1,0,1]
	v_pk_fma_f32 v[20:21], v[106:107], v[70:71], v[20:21] op_sel_hi:[1,0,1]
	v_pk_fma_f32 v[18:19], v[106:107], v[78:79], v[18:19] op_sel_hi:[1,0,1]
	v_pk_fma_f32 v[24:25], v[106:107], v[86:87], v[24:25] op_sel_hi:[1,0,1]
	v_pk_fma_f32 v[22:23], v[106:107], v[94:95], v[22:23] op_sel_hi:[1,0,1]
	s_waitcnt vmcnt(11)
; __device__ __forceinline__ void phase_init(const Frame& F, ArgsRef A) {
;     ...
; #pragma unroll 8
;         for (int k = 0; k < 256; ++k) { const f32x2 w = *(const f32x2*)(wp + (size_t)k * 18432);
; #pragma unroll
;             for (int bs = 0; bs < 9; ++bs) { const float s = sp[bs * 2048 + k]; a0[bs] += s * w.x; a1[bs] += s * w.y; } }
	v_pk_fma_f32 v[8:9], v[108:109], v[116:117], v[8:9] op_sel_hi:[1,0,1]
	v_pk_fma_f32 v[12:13], v[108:109], v[118:119], v[12:13] op_sel_hi:[1,0,1]
	v_pk_fma_f32 v[10:11], v[108:109], v[120:121], v[10:11] op_sel_hi:[1,0,1]
	v_pk_fma_f32 v[16:17], v[108:109], v[122:123], v[16:17] op_sel_hi:[1,0,1]
	v_pk_fma_f32 v[14:15], v[108:109], v[124:125], v[14:15] op_sel_hi:[1,0,1]
	v_pk_fma_f32 v[20:21], v[108:109], v[126:127], v[20:21] op_sel_hi:[1,0,1]
	v_pk_fma_f32 v[18:19], v[108:109], v[128:129], v[18:19] op_sel_hi:[1,0,1]
	v_pk_fma_f32 v[24:25], v[108:109], v[130:131], v[24:25] op_sel_hi:[1,0,1]
	v_pk_fma_f32 v[22:23], v[108:109], v[148:149], v[22:23] op_sel_hi:[1,0,1]
	v_pk_fma_f32 v[8:9], v[100:101], v[30:31], v[8:9] op_sel_hi:[1,0,1]
	v_pk_fma_f32 v[12:13], v[100:101], v[40:41], v[12:13] op_sel_hi:[1,0,1]
	v_pk_fma_f32 v[10:11], v[100:101], v[48:49], v[10:11] op_sel_hi:[1,0,1]
	v_pk_fma_f32 v[16:17], v[100:101], v[56:57], v[16:17] op_sel_hi:[1,0,1]
	v_pk_fma_f32 v[14:15], v[100:101], v[64:65], v[14:15] op_sel_hi:[1,0,1]
	v_pk_fma_f32 v[20:21], v[100:101], v[72:73], v[20:21] op_sel_hi:[1,0,1]
	v_pk_fma_f32 v[18:19], v[100:101], v[80:81], v[18:19] op_sel_hi:[1,0,1]
	v_pk_fma_f32 v[24:25], v[100:101], v[88:89], v[24:25] op_sel_hi:[1,0,1]
	v_pk_fma_f32 v[22:23], v[100:101], v[96:97], v[22:23] op_sel_hi:[1,0,1]
	s_waitcnt vmcnt(10)
	v_pk_fma_f32 v[8:9], v[110:111], v[30:31], v[8:9] op_sel:[0,1,0]
	v_pk_fma_f32 v[12:13], v[110:111], v[40:41], v[12:13] op_sel:[0,1,0]
	v_pk_fma_f32 v[10:11], v[110:111], v[48:49], v[10:11] op_sel:[0,1,0]
	v_pk_fma_f32 v[16:17], v[110:111], v[56:57], v[16:17] op_sel:[0,1,0]
	v_pk_fma_f32 v[14:15], v[110:111], v[64:65], v[14:15] op_sel:[0,1,0]
	v_pk_fma_f32 v[20:21], v[110:111], v[72:73], v[20:21] op_sel:[0,1,0]
	v_pk_fma_f32 v[18:19], v[110:111], v[80:81], v[18:19] op_sel:[0,1,0]
	v_pk_fma_f32 v[24:25], v[110:111], v[88:89], v[24:25] op_sel:[0,1,0]
	v_pk_fma_f32 v[22:23], v[110:111], v[96:97], v[22:23] op_sel:[0,1,0]
	s_waitcnt vmcnt(9)
	v_pk_fma_f32 v[8:9], v[112:113], v[32:33], v[8:9] op_sel_hi:[1,0,1]
	v_pk_fma_f32 v[12:13], v[112:113], v[42:43], v[12:13] op_sel_hi:[1,0,1]
	v_pk_fma_f32 v[10:11], v[112:113], v[50:51], v[10:11] op_sel_hi:[1,0,1]
	v_pk_fma_f32 v[16:17], v[112:113], v[58:59], v[16:17] op_sel_hi:[1,0,1]
	v_pk_fma_f32 v[14:15], v[112:113], v[66:67], v[14:15] op_sel_hi:[1,0,1]
	v_pk_fma_f32 v[20:21], v[112:113], v[74:75], v[20:21] op_sel_hi:[1,0,1]
	v_pk_fma_f32 v[18:19], v[112:113], v[82:83], v[18:19] op_sel_hi:[1,0,1]
	v_pk_fma_f32 v[24:25], v[112:113], v[90:91], v[24:25] op_sel_hi:[1,0,1]
	v_pk_fma_f32 v[22:23], v[112:113], v[98:99], v[22:23] op_sel_hi:[1,0,1]
	s_waitcnt vmcnt(8)
	v_pk_fma_f32 v[8:9], v[114:115], v[132:133], v[8:9] op_sel_hi:[1,0,1]
	v_pk_fma_f32 v[12:13], v[114:115], v[134:135], v[12:13] op_sel_hi:[1,0,1]
	v_pk_fma_f32 v[10:11], v[114:115], v[136:137], v[10:11] op_sel_hi:[1,0,1]
	v_pk_fma_f32 v[16:17], v[114:115], v[138:139], v[16:17] op_sel_hi:[1,0,1]
	v_pk_fma_f32 v[14:15], v[114:115], v[140:141], v[14:15] op_sel_hi:[1,0,1]
	v_pk_fma_f32 v[20:21], v[114:115], v[142:143], v[20:21] op_sel_hi:[1,0,1]
	v_pk_fma_f32 v[18:19], v[114:115], v[144:145], v[18:19] op_sel_hi:[1,0,1]
	v_pk_fma_f32 v[24:25], v[114:115], v[146:147], v[24:25] op_sel_hi:[1,0,1]
	v_pk_fma_f32 v[22:23], v[114:115], v[150:151], v[22:23] op_sel_hi:[1,0,1]
	s_add_i32 s9, s12, s8
	v_mov_b32_e32 v88, s9
	s_add_i32 s8, s8, 32
	s_add_i32 s2, s9, 0x10000
	s_add_i32 s3, s9, 0x10010
	v_mov_b32_e32 v92, s2
	v_mov_b32_e32 v96, s3
	ds_read_b128 v[26:29], v88
	ds_read_b128 v[30:33], v88 offset:16
	ds_read_b128 v[36:39], v88 offset:8192
	ds_read_b128 v[40:43], v88 offset:8208
	ds_read_b128 v[44:47], v88 offset:16384
	ds_read_b128 v[48:51], v88 offset:16400
	ds_read_b128 v[52:55], v88 offset:24576
	ds_read_b128 v[56:59], v88 offset:24592
	ds_read_b128 v[60:63], v88 offset:32768
	ds_read_b128 v[64:67], v88 offset:32784
	ds_read_b128 v[68:71], v88 offset:40960
	ds_read_b128 v[72:75], v88 offset:40976
	ds_read_b128 v[76:79], v88 offset:49152
	ds_read_b128 v[80:83], v88 offset:49168
	ds_read_b128 v[84:87], v88 offset:57344
	ds_read_b128 v[88:91], v88 offset:57360
	ds_read_b128 v[92:95], v92
	ds_read_b128 v[96:99], v96
	s_waitcnt lgkmcnt(14)
	v_mov_b32_e32 v116, v29
	v_mov_b32_e32 v118, v39
	s_waitcnt lgkmcnt(13)
	v_mov_b32_e32 v120, v47
	s_waitcnt lgkmcnt(11)
	v_mov_b32_e32 v122, v55
	s_waitcnt lgkmcnt(9)
	v_mov_b32_e32 v124, v63
	s_waitcnt lgkmcnt(7)
	v_mov_b32_e32 v126, v71
	s_waitcnt lgkmcnt(5)
	v_mov_b32_e32 v128, v79
	s_waitcnt lgkmcnt(3)
	v_mov_b32_e32 v130, v87
	s_waitcnt lgkmcnt(1)
	v_mov_b32_e32 v148, v95
	v_mov_b32_e32 v132, v33
	v_mov_b32_e32 v134, v43
	v_mov_b32_e32 v136, v51
	v_mov_b32_e32 v138, v59
	v_mov_b32_e32 v140, v67
	v_mov_b32_e32 v142, v75
	v_mov_b32_e32 v144, v83
	v_mov_b32_e32 v146, v91
	s_waitcnt lgkmcnt(0)
	v_mov_b32_e32 v150, v99
	v_lshl_add_u64 v[6:7], v[6:7], 0, s[4:5]
	s_cmpk_eq_i32 s8, 0x400
	s_waitcnt vmcnt(6)
	v_pk_fma_f32 v[8:9], v[154:155], v[26:27], v[8:9] op_sel_hi:[1,0,1]
	v_pk_fma_f32 v[12:13], v[154:155], v[36:37], v[12:13] op_sel_hi:[1,0,1]
	v_pk_fma_f32 v[10:11], v[154:155], v[44:45], v[10:11] op_sel_hi:[1,0,1]
	v_pk_fma_f32 v[16:17], v[154:155], v[52:53], v[16:17] op_sel_hi:[1,0,1]
	v_pk_fma_f32 v[14:15], v[154:155], v[60:61], v[14:15] op_sel_hi:[1,0,1]
	v_pk_fma_f32 v[20:21], v[154:155], v[68:69], v[20:21] op_sel_hi:[1,0,1]
	v_pk_fma_f32 v[18:19], v[154:155], v[76:77], v[18:19] op_sel_hi:[1,0,1]
	v_pk_fma_f32 v[24:25], v[154:155], v[84:85], v[24:25] op_sel_hi:[1,0,1]
	v_pk_fma_f32 v[22:23], v[154:155], v[92:93], v[22:23] op_sel_hi:[1,0,1]
	s_waitcnt vmcnt(5)
; __device__ __forceinline__ void phase_init(const Frame& F, ArgsRef A) {
;     ...
; #pragma unroll 8
;         for (int k = 0; k < 256; ++k) { const f32x2 w = *(const f32x2*)(wp + (size_t)k * 18432);
; #pragma unroll
;             for (int bs = 0; bs < 9; ++bs) { const float s = sp[bs * 2048 + k]; a0[bs] += s * w.x; a1[bs] += s * w.y; } }
; #pragma unroll
;         for (int bs = 0; bs < 9; ++bs) { red[(F.wave * 9 + bs) * 128 + 2 * F.lane] = a0[bs]; red[(F.wave * 9 + bs) * 128 + 2 * F.lane + 1] = a1[bs]; }
;         __syncthreads();
;         for (int o = F.tid; o < 9 * 128; o += NTHR) { const int bs = o >> 7, cc = o & 127; float s = ada_b[l * 18432 + cb * 128 + cc];
; #pragma unroll
;             for (int w = 0; w < 8; ++w) s += red[(w * 9 + bs) * 128 + cc];
;             mods[((size_t)l * 9 + bs) * 18432 + cb * 128 + cc] = s; }
	v_pk_fma_f32 v[8:9], v[156:157], v[26:27], v[8:9] op_sel:[0,1,0]
	v_pk_fma_f32 v[12:13], v[156:157], v[36:37], v[12:13] op_sel:[0,1,0]
	v_pk_fma_f32 v[10:11], v[156:157], v[44:45], v[10:11] op_sel:[0,1,0]
	v_pk_fma_f32 v[16:17], v[156:157], v[52:53], v[16:17] op_sel:[0,1,0]
	v_pk_fma_f32 v[14:15], v[156:157], v[60:61], v[14:15] op_sel:[0,1,0]
	v_pk_fma_f32 v[20:21], v[156:157], v[68:69], v[20:21] op_sel:[0,1,0]
	v_pk_fma_f32 v[18:19], v[156:157], v[76:77], v[18:19] op_sel:[0,1,0]
	v_pk_fma_f32 v[24:25], v[156:157], v[84:85], v[24:25] op_sel:[0,1,0]
	v_pk_fma_f32 v[22:23], v[156:157], v[92:93], v[22:23] op_sel:[0,1,0]
	s_waitcnt vmcnt(4)
	v_pk_fma_f32 v[8:9], v[158:159], v[28:29], v[8:9] op_sel_hi:[1,0,1]
	v_pk_fma_f32 v[12:13], v[158:159], v[38:39], v[12:13] op_sel_hi:[1,0,1]
	v_pk_fma_f32 v[10:11], v[158:159], v[46:47], v[10:11] op_sel_hi:[1,0,1]
	v_pk_fma_f32 v[16:17], v[158:159], v[54:55], v[16:17] op_sel_hi:[1,0,1]
	v_pk_fma_f32 v[14:15], v[158:159], v[62:63], v[14:15] op_sel_hi:[1,0,1]
	v_pk_fma_f32 v[20:21], v[158:159], v[70:71], v[20:21] op_sel_hi:[1,0,1]
	v_pk_fma_f32 v[18:19], v[158:159], v[78:79], v[18:19] op_sel_hi:[1,0,1]
	v_pk_fma_f32 v[24:25], v[158:159], v[86:87], v[24:25] op_sel_hi:[1,0,1]
	v_pk_fma_f32 v[22:23], v[158:159], v[94:95], v[22:23] op_sel_hi:[1,0,1]
	s_waitcnt vmcnt(3)
	v_pk_fma_f32 v[8:9], v[160:161], v[116:117], v[8:9] op_sel_hi:[1,0,1]
	v_pk_fma_f32 v[12:13], v[160:161], v[118:119], v[12:13] op_sel_hi:[1,0,1]
	v_pk_fma_f32 v[10:11], v[160:161], v[120:121], v[10:11] op_sel_hi:[1,0,1]
	v_pk_fma_f32 v[16:17], v[160:161], v[122:123], v[16:17] op_sel_hi:[1,0,1]
	v_pk_fma_f32 v[14:15], v[160:161], v[124:125], v[14:15] op_sel_hi:[1,0,1]
	v_pk_fma_f32 v[20:21], v[160:161], v[126:127], v[20:21] op_sel_hi:[1,0,1]
	v_pk_fma_f32 v[18:19], v[160:161], v[128:129], v[18:19] op_sel_hi:[1,0,1]
	v_pk_fma_f32 v[24:25], v[160:161], v[130:131], v[24:25] op_sel_hi:[1,0,1]
	v_pk_fma_f32 v[22:23], v[160:161], v[148:149], v[22:23] op_sel_hi:[1,0,1]
	v_pk_fma_f32 v[8:9], v[152:153], v[30:31], v[8:9] op_sel_hi:[1,0,1]
	v_pk_fma_f32 v[12:13], v[152:153], v[40:41], v[12:13] op_sel_hi:[1,0,1]
	v_pk_fma_f32 v[10:11], v[152:153], v[48:49], v[10:11] op_sel_hi:[1,0,1]
	v_pk_fma_f32 v[16:17], v[152:153], v[56:57], v[16:17] op_sel_hi:[1,0,1]
	v_pk_fma_f32 v[14:15], v[152:153], v[64:65], v[14:15] op_sel_hi:[1,0,1]
	v_pk_fma_f32 v[20:21], v[152:153], v[72:73], v[20:21] op_sel_hi:[1,0,1]
	v_pk_fma_f32 v[18:19], v[152:153], v[80:81], v[18:19] op_sel_hi:[1,0,1]
	v_pk_fma_f32 v[24:25], v[152:153], v[88:89], v[24:25] op_sel_hi:[1,0,1]
	v_pk_fma_f32 v[22:23], v[152:153], v[96:97], v[22:23] op_sel_hi:[1,0,1]
	s_waitcnt vmcnt(2)
	v_pk_fma_f32 v[8:9], v[162:163], v[30:31], v[8:9] op_sel:[0,1,0]
	v_pk_fma_f32 v[12:13], v[162:163], v[40:41], v[12:13] op_sel:[0,1,0]
	v_pk_fma_f32 v[10:11], v[162:163], v[48:49], v[10:11] op_sel:[0,1,0]
	v_pk_fma_f32 v[16:17], v[162:163], v[56:57], v[16:17] op_sel:[0,1,0]
	v_pk_fma_f32 v[14:15], v[162:163], v[64:65], v[14:15] op_sel:[0,1,0]
	v_pk_fma_f32 v[20:21], v[162:163], v[72:73], v[20:21] op_sel:[0,1,0]
	v_pk_fma_f32 v[18:19], v[162:163], v[80:81], v[18:19] op_sel:[0,1,0]
	v_pk_fma_f32 v[24:25], v[162:163], v[88:89], v[24:25] op_sel:[0,1,0]
	v_pk_fma_f32 v[22:23], v[162:163], v[96:97], v[22:23] op_sel:[0,1,0]
	s_waitcnt vmcnt(1)
	v_pk_fma_f32 v[8:9], v[164:165], v[32:33], v[8:9] op_sel_hi:[1,0,1]
	v_pk_fma_f32 v[12:13], v[164:165], v[42:43], v[12:13] op_sel_hi:[1,0,1]
	v_pk_fma_f32 v[10:11], v[164:165], v[50:51], v[10:11] op_sel_hi:[1,0,1]
	v_pk_fma_f32 v[16:17], v[164:165], v[58:59], v[16:17] op_sel_hi:[1,0,1]
	v_pk_fma_f32 v[14:15], v[164:165], v[66:67], v[14:15] op_sel_hi:[1,0,1]
	v_pk_fma_f32 v[20:21], v[164:165], v[74:75], v[20:21] op_sel_hi:[1,0,1]
	v_pk_fma_f32 v[18:19], v[164:165], v[82:83], v[18:19] op_sel_hi:[1,0,1]
	v_pk_fma_f32 v[24:25], v[164:165], v[90:91], v[24:25] op_sel_hi:[1,0,1]
	v_pk_fma_f32 v[22:23], v[164:165], v[98:99], v[22:23] op_sel_hi:[1,0,1]
	s_waitcnt vmcnt(0)
	v_pk_fma_f32 v[8:9], v[166:167], v[132:133], v[8:9] op_sel_hi:[1,0,1]
	v_pk_fma_f32 v[12:13], v[166:167], v[134:135], v[12:13] op_sel_hi:[1,0,1]
	v_pk_fma_f32 v[10:11], v[166:167], v[136:137], v[10:11] op_sel_hi:[1,0,1]
	v_pk_fma_f32 v[16:17], v[166:167], v[138:139], v[16:17] op_sel_hi:[1,0,1]
	v_pk_fma_f32 v[14:15], v[166:167], v[140:141], v[14:15] op_sel_hi:[1,0,1]
	v_pk_fma_f32 v[20:21], v[166:167], v[142:143], v[20:21] op_sel_hi:[1,0,1]
	v_pk_fma_f32 v[18:19], v[166:167], v[144:145], v[18:19] op_sel_hi:[1,0,1]
	v_pk_fma_f32 v[24:25], v[166:167], v[146:147], v[24:25] op_sel_hi:[1,0,1]
	v_pk_fma_f32 v[22:23], v[166:167], v[150:151], v[22:23] op_sel_hi:[1,0,1]
	s_cbranch_scc0 .LBB0_16
	ds_write2st64_b64 v2, v[8:9], v[12:13] offset1:1
	ds_write2st64_b64 v2, v[10:11], v[16:17] offset0:2 offset1:3
	ds_write2st64_b64 v2, v[14:15], v[20:21] offset0:4 offset1:5
	ds_write2st64_b64 v2, v[18:19], v[24:25] offset0:6 offset1:7
	ds_write_b64 v2, v[22:23] offset:4096
	s_waitcnt lgkmcnt(0)
	s_barrier
	s_and_saveexec_b64 s[8:9], vcc
	s_cbranch_execz .LBB0_14
	s_mul_i32 s2, s7, 0x4800
	s_add_i32 s2, s2, s6
	v_or_b32_e32 v6, s2, v34
	s_mul_hi_i32 s11, s7, 9
	s_mul_i32 s10, s7, 9
	s_ashr_i32 s7, s6, 31
	v_ashrrev_i32_e32 v7, 31, v6
	v_lshl_add_u64 v[6:7], v[6:7], 2, s[0:1]
	v_lshl_add_u64 v[8:9], s[6:7], 2, v[4:5]
	s_mov_b64 s[6:7], 0
	v_mov_b32_e32 v10, v0

;     ...
;     for (int m = gw; m < nrows; m += NGW) {
;         float* xr = xrow(F, m);
;         const float* xs = (m < ML) ? (src_l ? src_l + (size_t)m * D : xr) : (src_c ? src_c + (size_t)(m - ML) * D : xr);
;         f32x4 v[8];
; #pragma unroll
;         for (int j = 0; j < 8; ++j) v[j] = ((const f32x4*)xs)[F.lane + 64 * j];
;         if (POST && part != nullptr && m >= ML) {
;             const v2u* pp = (const v2u*)(part + (size_t)(m - ML) * D);
; #pragma unroll
;             for (int j = 0; j < 8; ++j) { const int o = F.lane + 64 * j; const v2u p0 = pp[o], p1 = pp[o + (size_t)MC * D / 4], p2 = pp[o + 2 * ((size_t)MC * D / 4)], p3 = pp[o + 3 * ((size_t)MC * D / 4)];
;                 const f32x4 ps = ((f32x4){bflo(p0.x), bfhi(p0.x), bflo(p0.y), bfhi(p0.y)} + (f32x4){bflo(p1.x), bfhi(p1.x), bflo(p1.y), bfhi(p1.y)}) + ((f32x4){bflo(p2.x), bfhi(p2.x), bflo(p2.y), bfhi(p2.y)} + (f32x4){bflo(p3.x), bfhi(p3.x), bflo(p3.y), bfhi(p3.y)});
;                 v[j] = v[j] * ALPHA + ((const f32x4*)pmod)[o] * pcoef * ps; }
;         }
;         if (POST) {
;             float s = 0.f;
; #pragma unroll
;             for (int j = 0; j < 8; ++j) s += (v[j].x + v[j].y) + (v[j].z + v[j].w);
;             const float mean = wave_sum(s) * (1.f / D); float s2 = 0.f;
; #pragma unroll
;             for (int j = 0; j < 8; ++j) { v[j] = v[j] - mean; s2 += (v[j].x * v[j].x + v[j].y * v[j].y) + (v[j].z * v[j].z + v[j].w * v[j].w); }
;             const float rstd = 1.f / sqrtf(wave_sum(s2) * (1.f / D) + LN_EPS);
; #pragma unroll
;             for (int j = 0; j < 8; ++j) { const f32x4 gg = ((const f32x4*)g)[F.lane + 64 * j], bb = ((const f32x4*)b)[F.lane + 64 * j]; v[j] = v[j] * rstd * gg + bb; if (WX || m >= ML) ((f32x4*)xr)[F.lane + 64 * j] = v[j]; }
;             if (!WX && m < ML && F.lane == 0) *(v2f*)(WSP(float, WS_STATS) + 2 * m) = (v2f){mean, rstd};
;         }
;         if (MODH) {
;             float s = 0.f;
; #pragma unroll
;             for (int j = 0; j < 8; ++j) s += (v[j].x + v[j].y) + (v[j].z + v[j].w);
;             const float mean = wave_sum(s) * (1.f / D); float s2 = 0.f;
; #pragma unroll
;             for (int j = 0; j < 8; ++j) { v[j] = v[j] - mean; s2 += (v[j].x * v[j].x + v[j].y * v[j].y) + (v[j].z * v[j].z + v[j].w * v[j].w); }
;             const float rstd = 1.f / sqrtf(wave_sum(s2) * (1.f / D) + LN_EPS);
;             const int bsel = m < ML ? (m >> 11) : 8;
.LBB0_70:
	s_add_i32 s2, s24, 0xffffc000
	s_cmpk_lt_i32 s24, 0x4000
	s_cselect_b32 s3, s25, 0
	s_cselect_b32 s2, s24, s2
	s_cselect_b32 s15, s16, s9
	s_cselect_b32 s27, s17, s26
	s_waitcnt lgkmcnt(0)
	s_cselect_b32 s28, s4, s20
	s_cselect_b32 s29, s5, s21
	s_lshl_b64 s[2:3], s[2:3], 13
	s_cmp_eq_u64 s[28:29], 0
	s_cselect_b32 s15, s15, s28
	s_cselect_b32 s27, s27, s29
	s_add_u32 s2, s15, s2
	s_addc_u32 s3, s27, s3
	v_lshl_add_u64 v[4:5], s[2:3], 0, v[34:35]
	global_load_dwordx4 v[42:45], v[4:5], off
	global_load_dwordx4 v[28:31], v[4:5], off offset:1024
	global_load_dwordx4 v[24:27], v[4:5], off offset:2048
	global_load_dwordx4 v[20:23], v[4:5], off offset:3072
	v_add_co_u32_e32 v4, vcc, s64, v4
	s_min_i32 s15, s24, 0x4000
	s_nop 0
	v_addc_co_u32_e32 v5, vcc, 0, v5, vcc
	global_load_dwordx4 v[16:19], v[4:5], off
	global_load_dwordx4 v[12:15], v[4:5], off offset:1024
	global_load_dwordx4 v[8:11], v[4:5], off offset:2048
	s_nop 0
	global_load_dwordx4 v[4:7], v[4:5], off offset:3072
	s_ashr_i32 s2, s15, 11
	s_mul_hi_i32 s3, s2, 0x12000
	s_mul_i32 s2, s2, 0x12000
	s_add_u32 s2, s18, s2
	s_addc_u32 s3, s19, s3
	v_lshl_add_u64 v[38:39], s[2:3], 0, v[34:35]
	v_add_co_u32_e32 v36, vcc, s83, v38
	v_mov_b32_e32 v1, v2
	s_nop 0
	v_addc_co_u32_e32 v37, vcc, 0, v39, vcc
	global_load_dwordx4 v[46:49], v[38:39], off
	global_load_dwordx4 v[50:53], v[36:37], off offset:-4096
	v_mov_b32_e32 v3, v2
	v_mov_b32_e32 v74, v2
	v_mov_b32_e32 v75, v2
	v_lshl_add_u64 v[40:41], v[38:39], 0, s[42:43]
	global_load_dwordx4 v[104:107], v[40:41], off offset:1024
	global_load_dwordx4 v[108:111], v[38:39], off offset:1024
	global_load_dwordx4 v[112:115], v[40:41], off offset:2048
	global_load_dwordx4 v[116:119], v[38:39], off offset:2048
	global_load_dwordx4 v[120:123], v[40:41], off offset:3072
	global_load_dwordx4 v[124:127], v[38:39], off offset:3072
	global_load_dwordx4 v[128:131], v[36:37], off
	global_load_dwordx4 v[132:135], v[40:41], off offset:-4096
	global_load_dwordx4 v[136:139], v[36:37], off offset:1024
	global_load_dwordx4 v[140:143], v[40:41], off offset:-3072
	global_load_dwordx4 v[144:147], v[36:37], off offset:2048
	global_load_dwordx4 v[148:151], v[40:41], off offset:-2048
	global_load_dwordx4 v[152:155], v[36:37], off offset:3072
	global_load_dwordx4 v[156:159], v[40:41], off offset:-1024
	s_add_u32 s24, s24, s12
	s_addc_u32 s25, s25, s13
	s_cmpk_lt_i32 s24, 0x4800
	s_waitcnt vmcnt(0)
	v_mov_b32_e32 v54, v42
	v_mov_b32_e32 v55, v28
	v_mov_b32_e32 v56, v43
	v_mov_b32_e32 v57, v29
	v_mov_b32_e32 v58, v44
	v_mov_b32_e32 v59, v30
	v_mov_b32_e32 v60, v45
	v_mov_b32_e32 v61, v31
	v_mov_b32_e32 v62, v25
	v_mov_b32_e32 v63, v26
	v_mov_b32_e32 v64, v24
	v_mov_b32_e32 v65, v27
	v_pk_add_f32 v[54:55], v[54:55], v[56:57]
	v_pk_add_f32 v[56:57], v[58:59], v[60:61]
	v_pk_add_f32 v[58:59], v[62:63], v[64:65]
	v_pk_add_f32 v[54:55], v[54:55], v[56:57]
	v_pk_add_f32 v[56:57], v[58:59], v[58:59] op_sel:[0,1] op_sel_hi:[1,0]
	v_add_f32_e32 v54, 0, v54
	v_add_f32_e32 v66, v20, v21
	v_add_f32_e32 v68, v22, v23
	v_mov_b32_e32 v61, v16
	v_mov_b32_e32 v67, v18
	v_mov_b32_e32 v69, v19
	v_mov_b32_e32 v57, v17
	v_add_f32_e32 v60, v54, v55
	v_mov_b32_e32 v62, v13
	v_mov_b32_e32 v63, v14
	v_mov_b32_e32 v64, v12
	v_mov_b32_e32 v65, v15
	v_pk_add_f32 v[58:59], v[66:67], v[68:69]
	v_pk_add_f32 v[54:55], v[60:61], v[56:57]
	v_pk_add_f32 v[62:63], v[62:63], v[64:65]
	v_pk_add_f32 v[54:55], v[54:55], v[58:59]
	v_pk_add_f32 v[62:63], v[62:63], v[62:63] op_sel:[0,1] op_sel_hi:[1,0]
	v_pk_add_f32 v[54:55], v[54:55], v[54:55] op_sel:[0,1] op_sel_hi:[1,0]
	v_add_f32_e32 v70, v8, v9
	v_add_f32_e32 v72, v10, v11
	v_mov_b32_e32 v71, v6
	v_mov_b32_e32 v73, v7
	v_mov_b32_e32 v63, v5
	v_mov_b32_e32 v55, v4
	v_pk_add_f32 v[64:65], v[70:71], v[72:73]
	v_pk_add_f32 v[54:55], v[54:55], v[62:63]
	v_pk_add_f32 v[52:53], v[52:53], 1.0 op_sel_hi:[1,0]
	v_pk_add_f32 v[54:55], v[54:55], v[64:65]
	v_pk_add_f32 v[50:51], v[50:51], 1.0 op_sel_hi:[1,0]
	v_add_f32_e32 v54, v54, v55
	s_nop 1
	v_add_f32_dpp v54, v54, v54 quad_perm:[1,0,3,2] row_mask:0xf bank_mask:0xf bound_ctrl:1
	s_nop 1
	v_add_f32_dpp v54, v54, v54 quad_perm:[2,3,0,1] row_mask:0xf bank_mask:0xf bound_ctrl:1
	s_nop 1
	v_add_f32_dpp v54, v54, v54 row_half_mirror row_mask:0xf bank_mask:0xf bound_ctrl:1
	s_nop 1
	v_add_f32_dpp v54, v54, v54 row_mirror row_mask:0xf bank_mask:0xf bound_ctrl:1
	s_nop 1
	v_mov_b32_dpp v1, v54 row_bcast:15 row_mask:0xa bank_mask:0xf
	v_add_f32_e32 v1, v54, v1
	s_nop 1
	v_mov_b32_dpp v3, v1 row_bcast:31 row_mask:0xc bank_mask:0xf
	v_add_f32_e32 v1, v1, v3
	s_nop 0
	v_readlane_b32 s2, v1, 63
	s_nop 1
	v_fma_f32 v45, s2, v224, v45
	v_fmac_f32_e32 v43, s2, v224
	v_fma_f32 v31, s2, v224, v31
	v_fmac_f32_e32 v29, s2, v224
	v_fma_f32 v44, s2, v224, v44
	v_fma_f32 v42, s2, v224, v42
	v_fma_f32 v30, s2, v224, v30
	v_fma_f32 v28, s2, v224, v28
	v_fma_f32 v55, s2, v224, v27
	v_fmac_f32_e32 v25, s2, v224
	v_fma_f32 v60, s2, v224, v14
	v_fma_f32 v61, s2, v224, v15
	v_mul_f32_e32 v1, v43, v43
	v_mul_f32_e32 v3, v45, v45
	v_mul_f32_e32 v14, v29, v29
	v_mul_f32_e32 v15, v31, v31
	v_fma_f32 v54, s2, v224, v26
	v_fma_f32 v24, s2, v224, v24
	v_fma_f32 v57, s2, v224, v23
	v_fmac_f32_e32 v21, s2, v224
	v_fma_f32 v58, s2, v224, v18
	v_fma_f32 v59, s2, v224, v19
	v_mul_f32_e32 v18, v25, v25
	v_mul_f32_e32 v19, v55, v55
	v_fmac_f32_e32 v1, v42, v42
	v_fmac_f32_e32 v3, v44, v44
	v_fmac_f32_e32 v14, v28, v28
	v_fmac_f32_e32 v15, v30, v30
	v_fma_f32 v56, s2, v224, v22
	v_fma_f32 v20, s2, v224, v20
	v_fmac_f32_e32 v17, s2, v224
	v_mul_f32_e32 v22, v21, v21
	v_mul_f32_e32 v23, v57, v57
	v_fmac_f32_e32 v18, v24, v24
	v_fmac_f32_e32 v19, v54, v54
; __device__ __forceinline__ unsigned pk2(float lo, float hi) { const f32x2 v = {lo, hi}; return __builtin_bit_cast(unsigned, __builtin_convertvector(v, bf2n_t_)); }
;     ...
;             const float mean = wave_sum(s) * (1.f / D); float s2 = 0.f;
; #pragma unroll
;             for (int j = 0; j < 8; ++j) { v[j] = v[j] - mean; s2 += (v[j].x * v[j].x + v[j].y * v[j].y) + (v[j].z * v[j].z + v[j].w * v[j].w); }
;             const float rstd = 1.f / sqrtf(wave_sum(s2) * (1.f / D) + LN_EPS);
;             const int bsel = m < ML ? (m >> 11) : 8;
;             const f32x4* shp = (const f32x4*)(mods_l + (size_t)bsel * 18432 + kshift * 2048);
;             const f32x4* scp = (const f32x4*)(mods_l + (size_t)bsel * 18432 + kscale * 2048);
;             v2u* hp = (v2u*)(HB + (size_t)m * D);
; #pragma unroll
;             for (int j = 0; j < 8; ++j) { const f32x4 sh = shp[F.lane + 64 * j], scl = scp[F.lane + 64 * j]; const f32x4 o = v[j] * rstd * (scl + 1.0f) + sh;
;                 v2u w; w.x = pk2(o.x, o.y); w.y = pk2(o.z, o.w); hp[F.lane + 64 * j] = w; }
	v_add_f32_e32 v1, v1, v3
	v_add_f32_e32 v3, v14, v15
	v_fma_f32 v16, s2, v224, v16
	v_fmac_f32_e32 v13, s2, v224
	v_mul_f32_e32 v26, v17, v17
	v_mul_f32_e32 v27, v59, v59
	v_fmac_f32_e32 v22, v20, v20
	v_fmac_f32_e32 v23, v56, v56
	v_add_f32_e32 v14, v18, v19
	v_add_f32_e32 v1, v1, v3
	v_fma_f32 v12, s2, v224, v12
	v_fma_f32 v11, s2, v224, v11
	v_fmac_f32_e32 v9, s2, v224
	v_mul_f32_e32 v62, v13, v13
	v_mul_f32_e32 v63, v61, v61
	v_fmac_f32_e32 v26, v16, v16
	v_fmac_f32_e32 v27, v58, v58
	v_add_f32_e32 v15, v22, v23
	v_add_f32_e32 v1, v14, v1
	v_fma_f32 v10, s2, v224, v10
	v_fma_f32 v8, s2, v224, v8
	v_fma_f32 v7, s2, v224, v7
	v_fmac_f32_e32 v5, s2, v224
	v_mul_f32_e32 v64, v9, v9
	v_mul_f32_e32 v65, v11, v11
	v_fmac_f32_e32 v62, v12, v12
	v_fmac_f32_e32 v63, v60, v60
	v_add_f32_e32 v18, v26, v27
	v_add_f32_e32 v1, v15, v1
	v_fma_f32 v6, s2, v224, v6
	v_fma_f32 v4, s2, v224, v4
	v_mul_f32_e32 v66, v5, v5
	v_mul_f32_e32 v67, v7, v7
	v_fmac_f32_e32 v64, v8, v8
	v_fmac_f32_e32 v65, v10, v10
	v_add_f32_e32 v19, v62, v63
	v_add_f32_e32 v1, v18, v1
	v_fmac_f32_e32 v66, v4, v4
	v_fmac_f32_e32 v67, v6, v6
	v_add_f32_e32 v22, v64, v65
	v_add_f32_e32 v1, v19, v1
	v_add_f32_e32 v23, v66, v67
	v_add_f32_e32 v1, v22, v1
	v_add_f32_e32 v1, v23, v1
	s_nop 1
	v_add_f32_dpp v1, v1, v1 quad_perm:[1,0,3,2] row_mask:0xf bank_mask:0xf bound_ctrl:1
	s_nop 1
	v_add_f32_dpp v1, v1, v1 quad_perm:[2,3,0,1] row_mask:0xf bank_mask:0xf bound_ctrl:1
	s_nop 1
	v_add_f32_dpp v1, v1, v1 row_half_mirror row_mask:0xf bank_mask:0xf bound_ctrl:1
	s_nop 1
	v_add_f32_dpp v1, v1, v1 row_mirror row_mask:0xf bank_mask:0xf bound_ctrl:1
	s_nop 1
	v_mov_b32_dpp v74, v1 row_bcast:15 row_mask:0xa bank_mask:0xf
	v_add_f32_e32 v1, v1, v74
	s_nop 1
	v_mov_b32_dpp v75, v1 row_bcast:31 row_mask:0xc bank_mask:0xf
	v_add_f32_e32 v1, v1, v75
	s_nop 0
	v_readlane_b32 s2, v1, 63
	s_nop 1
	v_fma_f32 v1, s2, v226, v225
	v_mul_f32_e32 v3, 0x4f800000, v1
	v_cmp_gt_f32_e32 vcc, s73, v1
	s_nop 1
	v_cndmask_b32_e32 v1, v1, v3, vcc
	v_sqrt_f32_e32 v3, v1
	s_nop 0
	v_add_u32_e32 v14, -1, v3
	v_add_u32_e32 v15, 1, v3
	v_fma_f32 v18, -v14, v3, v1
	v_fma_f32 v19, -v15, v3, v1
	v_cmp_ge_f32_e64 s[2:3], 0, v18
	s_nop 1
	v_cndmask_b32_e64 v3, v3, v14, s[2:3]
	v_cmp_lt_f32_e64 s[2:3], 0, v19
	s_nop 1
	v_cndmask_b32_e64 v3, v3, v15, s[2:3]
	v_mul_f32_e32 v14, 0x37800000, v3
	v_cndmask_b32_e32 v3, v3, v14, vcc
	v_cmp_class_f32_e32 vcc, v1, v227
	s_nop 1
	v_cndmask_b32_e32 v1, v3, v1, vcc
	v_div_scale_f32 v3, s[2:3], v1, v1, 1.0
	v_rcp_f32_e32 v15, v3
	v_div_scale_f32 v14, vcc, 1.0, v1, 1.0
	v_fma_f32 v18, -v3, v15, 1.0
	v_fmac_f32_e32 v15, v18, v15
	v_mul_f32_e32 v18, v14, v15
	v_fma_f32 v19, -v3, v18, v14
	v_fmac_f32_e32 v18, v19, v15
	v_fma_f32 v3, -v3, v18, v14
	v_div_fmas_f32 v3, v3, v15, v18
	v_div_fixup_f32 v62, v3, v1, 1.0
	v_pk_mul_f32 v[14:15], v[42:43], v[62:63] op_sel_hi:[1,0]
	v_pk_mul_f32 v[18:19], v[44:45], v[62:63] op_sel_hi:[1,0]
	v_pk_fma_f32 v[14:15], v[50:51], v[14:15], v[46:47]
	v_pk_fma_f32 v[18:19], v[52:53], v[18:19], v[48:49]
	v_cvt_pk_bf16_f32 v14, v14, v15
	v_cvt_pk_bf16_f32 v15, v18, v19
	global_store_dwordx2 v[32:33], v[14:15], off
	s_nop 0
	s_nop 0
	v_pk_mul_f32 v[14:15], v[28:29], v[62:63] op_sel_hi:[1,0]
	v_pk_mul_f32 v[18:19], v[30:31], v[62:63] op_sel_hi:[1,0]
	v_add_co_u32_e32 v30, vcc, s64, v38
	v_pk_mul_f32 v[12:13], v[12:13], v[62:63] op_sel_hi:[1,0]
	s_nop 0
	v_addc_co_u32_e32 v31, vcc, 0, v39, vcc
	v_pk_mul_f32 v[8:9], v[8:9], v[62:63] op_sel_hi:[1,0]
	v_pk_mul_f32 v[10:11], v[10:11], v[62:63] op_sel_hi:[1,0]
	v_pk_mul_f32 v[4:5], v[4:5], v[62:63] op_sel_hi:[1,0]
	v_pk_mul_f32 v[6:7], v[6:7], v[62:63] op_sel_hi:[1,0]
	s_nop 0
	v_pk_add_f32 v[22:23], v[106:107], 1.0 op_sel_hi:[1,0]
	v_pk_add_f32 v[26:27], v[104:105], 1.0 op_sel_hi:[1,0]
	s_nop 0
	v_pk_fma_f32 v[18:19], v[22:23], v[18:19], v[110:111]
	v_pk_fma_f32 v[14:15], v[26:27], v[14:15], v[108:109]
	s_nop 0
	v_cvt_pk_bf16_f32 v14, v14, v15
	v_cvt_pk_bf16_f32 v15, v18, v19
	global_store_dwordx2 v[32:33], v[14:15], off offset:512
	s_nop 0
	s_nop 0
	v_pk_mul_f32 v[14:15], v[24:25], v[62:63] op_sel_hi:[1,0]
	v_pk_mul_f32 v[18:19], v[54:55], v[62:63] op_sel_hi:[1,0]
	s_nop 0
	v_pk_add_f32 v[22:23], v[114:115], 1.0 op_sel_hi:[1,0]
	v_pk_add_f32 v[24:25], v[112:113], 1.0 op_sel_hi:[1,0]
	s_nop 0
	v_pk_fma_f32 v[18:19], v[18:19], v[22:23], v[118:119]
	v_pk_fma_f32 v[14:15], v[14:15], v[24:25], v[116:117]
	s_nop 0
	v_cvt_pk_bf16_f32 v14, v14, v15
	v_cvt_pk_bf16_f32 v15, v18, v19
	global_store_dwordx2 v[32:33], v[14:15], off offset:1024
	s_nop 0
	s_nop 0
	v_pk_mul_f32 v[14:15], v[20:21], v[62:63] op_sel_hi:[1,0]
	v_pk_mul_f32 v[18:19], v[56:57], v[62:63] op_sel_hi:[1,0]
	s_nop 0
	v_pk_add_f32 v[20:21], v[122:123], 1.0 op_sel_hi:[1,0]
	v_pk_add_f32 v[22:23], v[120:121], 1.0 op_sel_hi:[1,0]
	s_nop 0
	v_pk_fma_f32 v[18:19], v[18:19], v[20:21], v[126:127]
	v_pk_fma_f32 v[14:15], v[14:15], v[22:23], v[124:125]
	s_nop 0
	v_cvt_pk_bf16_f32 v14, v14, v15
	v_cvt_pk_bf16_f32 v15, v18, v19
	global_store_dwordx2 v[32:33], v[14:15], off offset:1536
	s_nop 0
	s_nop 0
	v_pk_mul_f32 v[14:15], v[16:17], v[62:63] op_sel_hi:[1,0]
	v_pk_mul_f32 v[16:17], v[58:59], v[62:63] op_sel_hi:[1,0]
	s_nop 0
	v_pk_add_f32 v[20:21], v[130:131], 1.0 op_sel_hi:[1,0]
	v_pk_add_f32 v[18:19], v[128:129], 1.0 op_sel_hi:[1,0]
	s_nop 0
	v_pk_fma_f32 v[16:17], v[16:17], v[20:21], v[134:135]
	v_pk_fma_f32 v[14:15], v[14:15], v[18:19], v[132:133]
	v_pk_mul_f32 v[22:23], v[60:61], v[62:63] op_sel_hi:[1,0]
	v_cvt_pk_bf16_f32 v14, v14, v15
	v_cvt_pk_bf16_f32 v15, v16, v17
	global_store_dwordx2 v[32:33], v[14:15], off offset:2048
	s_nop 0
	s_nop 0
	s_nop 0
	s_nop 0
	v_pk_add_f32 v[16:17], v[138:139], 1.0 op_sel_hi:[1,0]
	v_pk_add_f32 v[14:15], v[136:137], 1.0 op_sel_hi:[1,0]
	s_nop 0
	v_pk_fma_f32 v[16:17], v[22:23], v[16:17], v[142:143]
	v_pk_fma_f32 v[12:13], v[12:13], v[14:15], v[140:141]
	s_nop 0
	v_cvt_pk_bf16_f32 v12, v12, v13
	v_cvt_pk_bf16_f32 v13, v16, v17
	global_store_dwordx2 v[32:33], v[12:13], off offset:2560
	s_nop 0
	s_nop 0
	s_nop 0
	s_nop 0
	v_pk_add_f32 v[14:15], v[146:147], 1.0 op_sel_hi:[1,0]
	v_pk_add_f32 v[12:13], v[144:145], 1.0 op_sel_hi:[1,0]
	s_nop 0
	v_pk_fma_f32 v[10:11], v[10:11], v[14:15], v[150:151]
	v_pk_fma_f32 v[8:9], v[8:9], v[12:13], v[148:149]
	s_nop 0
	v_cvt_pk_bf16_f32 v8, v8, v9
	v_cvt_pk_bf16_f32 v9, v10, v11
	global_store_dwordx2 v[32:33], v[8:9], off offset:3072
	s_nop 0
	s_nop 0
	s_nop 0
	s_nop 0
	v_pk_add_f32 v[10:11], v[154:155], 1.0 op_sel_hi:[1,0]
	v_pk_add_f32 v[8:9], v[152:153], 1.0 op_sel_hi:[1,0]
	s_nop 0
	v_pk_fma_f32 v[6:7], v[6:7], v[10:11], v[158:159]
	v_pk_fma_f32 v[4:5], v[4:5], v[8:9], v[156:157]
	s_nop 0
	v_cvt_pk_bf16_f32 v4, v4, v5
	v_cvt_pk_bf16_f32 v5, v6, v7
	global_store_dwordx2 v[32:33], v[4:5], off offset:3584
	v_lshl_add_u64 v[32:33], v[32:33], 0, s[22:23]
	s_cbranch_scc1 .LBB0_70

; __device__ __forceinline__ unsigned pk2(float lo, float hi) { const f32x2 v = {lo, hi}; return __builtin_bit_cast(unsigned, __builtin_convertvector(v, bf2n_t_)); }
;     ...
;         if (MODH) {
;             float s = 0.f;
; #pragma unroll
;             for (int j = 0; j < 8; ++j) s += (v[j].x + v[j].y) + (v[j].z + v[j].w);
;             const float mean = wave_sum(s) * (1.f / D); float s2 = 0.f;
; #pragma unroll
;             for (int j = 0; j < 8; ++j) { v[j] = v[j] - mean; s2 += (v[j].x * v[j].x + v[j].y * v[j].y) + (v[j].z * v[j].z + v[j].w * v[j].w); }
;             const float rstd = 1.f / sqrtf(wave_sum(s2) * (1.f / D) + LN_EPS);
;             const int bsel = m < ML ? (m >> 11) : 8;
;             const f32x4* shp = (const f32x4*)(mods_l + (size_t)bsel * 18432 + kshift * 2048);
;             const f32x4* scp = (const f32x4*)(mods_l + (size_t)bsel * 18432 + kscale * 2048);
;             v2u* hp = (v2u*)(HB + (size_t)m * D);
; #pragma unroll
;             for (int j = 0; j < 8; ++j) { const f32x4 sh = shp[F.lane + 64 * j], scl = scp[F.lane + 64 * j]; const f32x4 o = v[j] * rstd * (scl + 1.0f) + sh;
;                 v2u w; w.x = pk2(o.x, o.y); w.y = pk2(o.z, o.w); hp[F.lane + 64 * j] = w; }
.LBB0_75:
	s_or_b64 exec, exec, s[4:5]
	v_mov_b32_e32 v12, v32
	v_mov_b32_e32 v13, v26
	v_mov_b32_e32 v30, v33
	v_mov_b32_e32 v31, v27
	v_pk_add_f32 v[12:13], v[12:13], v[30:31]
	v_mov_b32_e32 v30, v34
	v_mov_b32_e32 v31, v28
	v_mov_b32_e32 v56, v35
	v_mov_b32_e32 v57, v29
	v_pk_add_f32 v[30:31], v[30:31], v[56:57]
	v_mov_b32_e32 v56, v36
	v_pk_add_f32 v[12:13], v[12:13], v[30:31]
	v_mov_b32_e32 v30, v37
	v_mov_b32_e32 v31, v38
	v_mov_b32_e32 v57, v39
	v_pk_add_f32 v[30:31], v[30:31], v[56:57]
	v_add_f32_e32 v3, 0, v12
	v_pk_add_f32 v[30:31], v[30:31], v[30:31] op_sel:[0,1] op_sel_hi:[1,0]
	v_add_f32_e32 v12, v3, v13
	v_add_f32_e32 v56, v22, v23
	v_add_f32_e32 v58, v24, v25
	v_mov_b32_e32 v13, v14
	v_mov_b32_e32 v31, v15
	v_mov_b32_e32 v57, v16
	v_mov_b32_e32 v59, v17
	v_pk_add_f32 v[12:13], v[12:13], v[30:31]
	v_pk_add_f32 v[30:31], v[56:57], v[58:59]
	v_mov_b32_e32 v56, v18
	v_pk_add_f32 v[12:13], v[12:13], v[30:31]
	v_mov_b32_e32 v30, v19
	v_mov_b32_e32 v31, v20
	v_mov_b32_e32 v57, v21
	v_pk_add_f32 v[30:31], v[30:31], v[56:57]
	v_pk_add_f32 v[12:13], v[12:13], v[12:13] op_sel:[0,1] op_sel_hi:[1,0]
	v_pk_add_f32 v[30:31], v[30:31], v[30:31] op_sel:[0,1] op_sel_hi:[1,0]
	v_add_f32_e32 v56, v8, v9
	v_add_f32_e32 v58, v10, v11
	v_mov_b32_e32 v13, v4
	v_mov_b32_e32 v31, v5
	v_mov_b32_e32 v57, v6
	v_mov_b32_e32 v59, v7
	v_pk_add_f32 v[12:13], v[12:13], v[30:31]
	v_pk_add_f32 v[30:31], v[56:57], v[58:59]
	s_min_i32 s4, s26, 0x4000
	v_pk_add_f32 v[12:13], v[12:13], v[30:31]
	s_ashr_i32 s4, s4, 11
	v_add_f32_e32 v3, v12, v13
	v_mov_b32_e32 v12, v2
	s_mul_hi_i32 s5, s4, 0x12000
	v_add_f32_dpp v3, v3, v3 quad_perm:[1,0,3,2] row_mask:0xf bank_mask:0xf bound_ctrl:1
	s_mul_i32 s4, s4, 0x12000
	s_add_u32 s4, s18, s4
	v_add_f32_dpp v3, v3, v3 quad_perm:[2,3,0,1] row_mask:0xf bank_mask:0xf bound_ctrl:1
	s_addc_u32 s5, s19, s5
	s_add_u32 s26, s26, s12
	v_add_f32_dpp v3, v3, v3 row_half_mirror row_mask:0xf bank_mask:0xf bound_ctrl:1
	s_addc_u32 s27, s27, s13
	s_add_i32 s22, s22, s40
	v_add_f32_dpp v3, v3, v3 row_mirror row_mask:0xf bank_mask:0xf bound_ctrl:1
	s_cmpk_gt_i32 s26, 0x47ff
	s_nop 0
	v_mov_b32_dpp v12, v3 row_bcast:15 row_mask:0xa bank_mask:0xf
	v_add_f32_e32 v3, v3, v12
	v_mov_b32_e32 v12, v2
	s_nop 1
	v_mov_b32_dpp v12, v3 row_bcast:31 row_mask:0xc bank_mask:0xf
	v_add_f32_e32 v3, v3, v12
	s_nop 0
	v_readlane_b32 s15, v3, 63
	s_nop 1
	v_fmac_f32_e32 v35, s15, v224
	v_fmac_f32_e32 v33, s15, v224
	v_fma_f32 v34, s15, v224, v34
	v_fma_f32 v32, s15, v224, v32
	v_mul_f32_e32 v3, v33, v33
	v_mul_f32_e32 v12, v35, v35
	v_fmac_f32_e32 v3, v32, v32
	v_fmac_f32_e32 v12, v34, v34
	v_fmac_f32_e32 v29, s15, v224
	v_fmac_f32_e32 v27, s15, v224
	v_add_f32_e32 v3, v3, v12
	v_fma_f32 v28, s15, v224, v28
	v_fma_f32 v26, s15, v224, v26
	v_mul_f32_e32 v12, v27, v27
	v_mul_f32_e32 v13, v29, v29
	v_fmac_f32_e32 v12, v26, v26
	v_fmac_f32_e32 v13, v28, v28
	v_add_f32_e32 v12, v12, v13
	v_fmac_f32_e32 v39, s15, v224
	v_fmac_f32_e32 v37, s15, v224
	v_add_f32_e32 v3, v3, v12
	v_fma_f32 v38, s15, v224, v38
	v_fma_f32 v36, s15, v224, v36
	v_mul_f32_e32 v12, v37, v37
	v_mul_f32_e32 v13, v39, v39
	v_fmac_f32_e32 v12, v36, v36
	v_fmac_f32_e32 v13, v38, v38
	v_add_f32_e32 v12, v12, v13
	v_fmac_f32_e32 v25, s15, v224
	v_fmac_f32_e32 v23, s15, v224
	v_add_f32_e32 v3, v12, v3
	v_fma_f32 v24, s15, v224, v24
	v_fma_f32 v22, s15, v224, v22
	v_mul_f32_e32 v12, v23, v23
	v_mul_f32_e32 v13, v25, v25
	v_fmac_f32_e32 v12, v22, v22
	v_fmac_f32_e32 v13, v24, v24
	v_add_f32_e32 v12, v12, v13
	v_fmac_f32_e32 v17, s15, v224
	v_fmac_f32_e32 v15, s15, v224
	v_add_f32_e32 v3, v12, v3
	v_fma_f32 v16, s15, v224, v16
	v_fma_f32 v14, s15, v224, v14
	v_mul_f32_e32 v12, v15, v15
	v_mul_f32_e32 v13, v17, v17
	v_fmac_f32_e32 v12, v14, v14
	v_fmac_f32_e32 v13, v16, v16
	v_add_f32_e32 v12, v12, v13
	v_add_f32_e32 v3, v12, v3
	v_lshl_add_u64 v[12:13], v[0:1], 4, s[4:5]
	v_add_co_u32_e32 v64, vcc, s83, v12
	v_fmac_f32_e32 v21, s15, v224
	s_nop 0
	v_addc_co_u32_e32 v65, vcc, 0, v13, vcc
	global_load_dwordx4 v[56:59], v[12:13], off
	global_load_dwordx4 v[60:63], v[64:65], off offset:-4096
	v_lshl_add_u64 v[248:249], v[12:13], 0, s[42:43]
	global_load_dwordx4 v[104:107], v[248:249], off offset:1024
	global_load_dwordx4 v[108:111], v[12:13], off offset:1024
	global_load_dwordx4 v[112:115], v[248:249], off offset:2048
	global_load_dwordx4 v[116:119], v[12:13], off offset:2048
	global_load_dwordx4 v[120:123], v[248:249], off offset:3072
	global_load_dwordx4 v[124:127], v[12:13], off offset:3072
	global_load_dwordx4 v[128:131], v[64:65], off
	global_load_dwordx4 v[132:135], v[248:249], off offset:-4096
	global_load_dwordx4 v[136:139], v[64:65], off offset:1024
	global_load_dwordx4 v[140:143], v[248:249], off offset:-3072
	global_load_dwordx4 v[144:147], v[64:65], off offset:2048
	global_load_dwordx4 v[148:151], v[248:249], off offset:-2048
	global_load_dwordx4 v[152:155], v[64:65], off offset:3072
	global_load_dwordx4 v[156:159], v[248:249], off offset:-1024
	v_fmac_f32_e32 v19, s15, v224
	v_fma_f32 v20, s15, v224, v20
	v_fma_f32 v18, s15, v224, v18
	v_mul_f32_e32 v30, v19, v19
	v_mul_f32_e32 v31, v21, v21
	v_fmac_f32_e32 v30, v18, v18
	v_fmac_f32_e32 v31, v20, v20
	v_add_f32_e32 v30, v30, v31
	v_fmac_f32_e32 v11, s15, v224
	v_fmac_f32_e32 v9, s15, v224
	v_add_f32_e32 v3, v30, v3
	v_fma_f32 v10, s15, v224, v10
	v_fma_f32 v8, s15, v224, v8
	v_mul_f32_e32 v30, v9, v9
	v_mul_f32_e32 v31, v11, v11
	v_fmac_f32_e32 v30, v8, v8
	v_fmac_f32_e32 v31, v10, v10
	v_add_f32_e32 v30, v30, v31
	v_fmac_f32_e32 v7, s15, v224
	v_fmac_f32_e32 v5, s15, v224
	v_add_f32_e32 v3, v30, v3
	v_fma_f32 v6, s15, v224, v6
	v_fma_f32 v4, s15, v224, v4
	v_mul_f32_e32 v30, v5, v5
	v_mul_f32_e32 v31, v7, v7
	v_fmac_f32_e32 v30, v4, v4
	v_fmac_f32_e32 v31, v6, v6
	v_add_f32_e32 v30, v30, v31
	v_add_f32_e32 v3, v30, v3
	v_mov_b32_e32 v30, v2
	s_waitcnt vmcnt(14)
; __device__ __forceinline__ unsigned pk2(float lo, float hi) { const f32x2 v = {lo, hi}; return __builtin_bit_cast(unsigned, __builtin_convertvector(v, bf2n_t_)); }
;     ...
;             const float rstd = 1.f / sqrtf(wave_sum(s2) * (1.f / D) + LN_EPS);
;             const int bsel = m < ML ? (m >> 11) : 8;
;             const f32x4* shp = (const f32x4*)(mods_l + (size_t)bsel * 18432 + kshift * 2048);
;             const f32x4* scp = (const f32x4*)(mods_l + (size_t)bsel * 18432 + kscale * 2048);
;             v2u* hp = (v2u*)(HB + (size_t)m * D);
; #pragma unroll
;             for (int j = 0; j < 8; ++j) { const f32x4 sh = shp[F.lane + 64 * j], scl = scp[F.lane + 64 * j]; const f32x4 o = v[j] * rstd * (scl + 1.0f) + sh;
;                 v2u w; w.x = pk2(o.x, o.y); w.y = pk2(o.z, o.w); hp[F.lane + 64 * j] = w; }
	v_pk_add_f32 v[60:61], v[60:61], 1.0 op_sel_hi:[1,0]
	v_add_f32_dpp v3, v3, v3 quad_perm:[1,0,3,2] row_mask:0xf bank_mask:0xf bound_ctrl:1
	s_nop 1
	v_add_f32_dpp v3, v3, v3 quad_perm:[2,3,0,1] row_mask:0xf bank_mask:0xf bound_ctrl:1
	s_nop 1
	v_add_f32_dpp v3, v3, v3 row_half_mirror row_mask:0xf bank_mask:0xf bound_ctrl:1
	s_nop 1
	v_add_f32_dpp v3, v3, v3 row_mirror row_mask:0xf bank_mask:0xf bound_ctrl:1
	s_nop 1
	v_mov_b32_dpp v30, v3 row_bcast:15 row_mask:0xa bank_mask:0xf
	v_add_f32_e32 v3, v3, v30
	v_mov_b32_e32 v30, v2
	s_nop 1
	v_mov_b32_dpp v30, v3 row_bcast:31 row_mask:0xc bank_mask:0xf
	v_add_f32_e32 v3, v3, v30
	s_nop 0
	v_readlane_b32 s4, v3, 63
	s_nop 1
	v_fma_f32 v3, s4, v226, v225
	v_mul_f32_e32 v30, 0x4f800000, v3
	v_cmp_gt_f32_e32 vcc, s73, v3
	s_nop 1
	v_cndmask_b32_e32 v3, v3, v30, vcc
	v_sqrt_f32_e32 v30, v3
	s_nop 0
	v_add_u32_e32 v31, -1, v30
	v_fma_f32 v66, -v31, v30, v3
	v_cmp_ge_f32_e64 s[4:5], 0, v66
	v_add_u32_e32 v66, 1, v30
	s_nop 0
	v_cndmask_b32_e64 v31, v30, v31, s[4:5]
	v_fma_f32 v30, -v66, v30, v3
	v_cmp_lt_f32_e64 s[4:5], 0, v30
	s_nop 1
	v_cndmask_b32_e64 v30, v31, v66, s[4:5]
	v_mul_f32_e32 v31, 0x37800000, v30
	v_cndmask_b32_e32 v30, v30, v31, vcc
	v_cmp_class_f32_e32 vcc, v3, v227
	s_nop 1
	v_cndmask_b32_e32 v3, v30, v3, vcc
	v_div_scale_f32 v30, s[4:5], v3, v3, 1.0
	v_rcp_f32_e32 v31, v30
	s_nop 0
	v_fma_f32 v66, -v30, v31, 1.0
	v_fmac_f32_e32 v31, v66, v31
	v_div_scale_f32 v66, vcc, 1.0, v3, 1.0
	v_mul_f32_e32 v67, v66, v31
	v_fma_f32 v68, -v30, v67, v66
	v_fmac_f32_e32 v67, v68, v31
	v_fma_f32 v30, -v30, v67, v66
	v_div_fmas_f32 v30, v30, v31, v67
	v_div_fixup_f32 v66, v30, v3, 1.0
	v_pk_mul_f32 v[30:31], v[32:33], v[66:67] op_sel_hi:[1,0]
	v_pk_mul_f32 v[32:33], v[34:35], v[66:67] op_sel_hi:[1,0]
	v_pk_add_f32 v[34:35], v[62:63], 1.0 op_sel_hi:[1,0]
	v_pk_fma_f32 v[30:31], v[60:61], v[30:31], v[56:57]
	v_pk_fma_f32 v[32:33], v[34:35], v[32:33], v[58:59]
	v_cvt_pk_bf16_f32 v30, v30, v31
	v_cvt_pk_bf16_f32 v31, v32, v33
	v_lshl_add_u64 v[68:69], v[12:13], 0, s[42:43]
	global_store_dwordx2 v[54:55], v[30:31], off
	s_nop 0
	s_nop 0
	s_nop 0
	v_pk_mul_f32 v[26:27], v[26:27], v[66:67] op_sel_hi:[1,0]
	v_pk_mul_f32 v[28:29], v[28:29], v[66:67] op_sel_hi:[1,0]
	v_pk_mul_f32 v[34:35], v[36:37], v[66:67] op_sel_hi:[1,0]
	v_pk_mul_f32 v[36:37], v[38:39], v[66:67] op_sel_hi:[1,0]
	v_pk_mul_f32 v[22:23], v[22:23], v[66:67] op_sel_hi:[1,0]
	v_pk_mul_f32 v[24:25], v[24:25], v[66:67] op_sel_hi:[1,0]
	v_pk_mul_f32 v[8:9], v[8:9], v[66:67] op_sel_hi:[1,0]
	v_pk_mul_f32 v[10:11], v[10:11], v[66:67] op_sel_hi:[1,0]
	v_pk_mul_f32 v[4:5], v[4:5], v[66:67] op_sel_hi:[1,0]
	v_pk_mul_f32 v[6:7], v[6:7], v[66:67] op_sel_hi:[1,0]
	s_waitcnt vmcnt(14)
	v_pk_add_f32 v[32:33], v[106:107], 1.0 op_sel_hi:[1,0]
	v_pk_add_f32 v[30:31], v[104:105], 1.0 op_sel_hi:[1,0]
	s_waitcnt vmcnt(13)
	v_pk_fma_f32 v[28:29], v[32:33], v[28:29], v[110:111]
	v_pk_fma_f32 v[26:27], v[30:31], v[26:27], v[108:109]
	s_nop 0
	v_cvt_pk_bf16_f32 v26, v26, v27
	v_cvt_pk_bf16_f32 v27, v28, v29
	global_store_dwordx2 v[54:55], v[26:27], off offset:512
	s_nop 0
	s_nop 0
	s_nop 0
	s_waitcnt vmcnt(13)
	v_pk_add_f32 v[28:29], v[114:115], 1.0 op_sel_hi:[1,0]
	v_pk_add_f32 v[26:27], v[112:113], 1.0 op_sel_hi:[1,0]
	s_waitcnt vmcnt(12)
	v_pk_fma_f32 v[28:29], v[36:37], v[28:29], v[118:119]
	v_pk_fma_f32 v[26:27], v[34:35], v[26:27], v[116:117]
	s_nop 0
	v_cvt_pk_bf16_f32 v26, v26, v27
	v_cvt_pk_bf16_f32 v27, v28, v29
	global_store_dwordx2 v[54:55], v[26:27], off offset:1024
	s_nop 0
	s_nop 0
	s_nop 0
	s_waitcnt vmcnt(12)
	v_pk_add_f32 v[28:29], v[122:123], 1.0 op_sel_hi:[1,0]
	v_pk_add_f32 v[26:27], v[120:121], 1.0 op_sel_hi:[1,0]
	s_waitcnt vmcnt(11)
	v_pk_fma_f32 v[24:25], v[24:25], v[28:29], v[126:127]
	v_pk_fma_f32 v[22:23], v[22:23], v[26:27], v[124:125]
	v_add_co_u32_e32 v30, vcc, s64, v12
	v_cvt_pk_bf16_f32 v22, v22, v23
	v_cvt_pk_bf16_f32 v23, v24, v25
	global_store_dwordx2 v[54:55], v[22:23], off offset:1536
	s_nop 0
	v_addc_co_u32_e32 v31, vcc, 0, v13, vcc
	s_nop 0
	v_pk_mul_f32 v[12:13], v[14:15], v[66:67] op_sel_hi:[1,0]
	v_pk_mul_f32 v[14:15], v[16:17], v[66:67] op_sel_hi:[1,0]
	s_waitcnt vmcnt(11)
	v_pk_add_f32 v[16:17], v[130:131], 1.0 op_sel_hi:[1,0]
	v_pk_add_f32 v[22:23], v[128:129], 1.0 op_sel_hi:[1,0]
	s_waitcnt vmcnt(10)
	v_pk_fma_f32 v[14:15], v[14:15], v[16:17], v[134:135]
	v_pk_fma_f32 v[12:13], v[12:13], v[22:23], v[132:133]
	v_pk_mul_f32 v[16:17], v[18:19], v[66:67] op_sel_hi:[1,0]
	v_cvt_pk_bf16_f32 v12, v12, v13
	v_cvt_pk_bf16_f32 v13, v14, v15
	global_store_dwordx2 v[54:55], v[12:13], off offset:2048
	s_nop 0
	s_nop 0
	s_nop 0
	v_pk_mul_f32 v[18:19], v[20:21], v[66:67] op_sel_hi:[1,0]
	s_waitcnt vmcnt(10)
	v_pk_add_f32 v[14:15], v[138:139], 1.0 op_sel_hi:[1,0]
	v_pk_add_f32 v[12:13], v[136:137], 1.0 op_sel_hi:[1,0]
	s_waitcnt vmcnt(9)
	v_pk_fma_f32 v[14:15], v[18:19], v[14:15], v[142:143]
	v_pk_fma_f32 v[12:13], v[16:17], v[12:13], v[140:141]
	s_nop 0
	v_cvt_pk_bf16_f32 v12, v12, v13
	v_cvt_pk_bf16_f32 v13, v14, v15
	global_store_dwordx2 v[54:55], v[12:13], off offset:2560
	s_nop 0
	s_nop 0
	s_nop 0
	s_waitcnt vmcnt(9)
	v_pk_add_f32 v[14:15], v[146:147], 1.0 op_sel_hi:[1,0]
	v_pk_add_f32 v[12:13], v[144:145], 1.0 op_sel_hi:[1,0]
	s_waitcnt vmcnt(8)
	v_pk_fma_f32 v[10:11], v[10:11], v[14:15], v[150:151]
	v_pk_fma_f32 v[8:9], v[8:9], v[12:13], v[148:149]
	s_nop 0
	v_cvt_pk_bf16_f32 v8, v8, v9
	v_cvt_pk_bf16_f32 v9, v10, v11
	global_store_dwordx2 v[54:55], v[8:9], off offset:3072
	s_nop 0
	s_nop 0
	s_nop 0
	s_waitcnt vmcnt(8)
	v_pk_add_f32 v[10:11], v[154:155], 1.0 op_sel_hi:[1,0]
	v_pk_add_f32 v[8:9], v[152:153], 1.0 op_sel_hi:[1,0]
	s_waitcnt vmcnt(7)
	v_pk_fma_f32 v[6:7], v[6:7], v[10:11], v[158:159]
	v_pk_fma_f32 v[4:5], v[4:5], v[8:9], v[156:157]
	s_nop 0
	v_cvt_pk_bf16_f32 v4, v4, v5
	v_cvt_pk_bf16_f32 v5, v6, v7
	global_store_dwordx2 v[54:55], v[4:5], off offset:3584
	v_lshl_add_u64 v[54:55], v[54:55], 0, s[24:25]
	s_cbranch_scc1 .LBB0_97
